# attention QK block software-pipelined: 4-slot K-fragment ring, 3 LDS reads in flight ahead of each MFMA
# speedup vs baseline: 1.0157x; 1.0001x over previous
.LBB0_725:
	s_not_b32 s24, s39
	s_lshl_b32 s31, s24, 3
	s_and_b32 s30, s31, 8
	s_waitcnt lgkmcnt(0)
	v_readlane_b32 s54, v254, 54
	v_readlane_b32 s55, v254, 55
	s_and_b64 s[54:55], exec, s[54:55]
	s_cbranch_scc0 .Lattn_qk_odd
	v_mov_b32_e32 v66, 0
	v_mov_b32_e32 v67, 0
	v_mov_b32_e32 v68, 0
	v_mov_b32_e32 v69, 0
	v_bitop3_b32 v232, s31, v111, 8 bitop3:0x6c
	v_lshlrev_b32_e32 v178, 4, v232
	v_or_b32_e32 v232, v178, v107
	v_mad_u32_u24 v226, v232, s96, v106
	ds_read_b128 v[204:207], v226
	ds_read_b128 v[208:211], v226 offset:64
	ds_read_b128 v[212:215], v226 offset:128
	ds_read_b128 v[216:219], v226 offset:192
	s_waitcnt lgkmcnt(3)
	v_mfma_f32_16x16x32_bf16 v[70:73], v[204:207], v[62:65], 0
	v_xor_b32_e32 v232, s30, v124
	v_lshl_or_b32 v232, v232, 4, v107
	v_mad_u32_u24 v227, v232, s96, v106
	ds_read_b128 v[204:207], v227
	s_waitcnt lgkmcnt(3)
	v_mfma_f32_16x16x32_bf16 v[70:73], v[208:211], v[58:61], v[70:73]
	ds_read_b128 v[208:211], v227 offset:64
	s_waitcnt lgkmcnt(3)
	v_mfma_f32_16x16x32_bf16 v[70:73], v[212:215], v[54:57], v[70:73]
	ds_read_b128 v[212:215], v227 offset:128
	s_waitcnt lgkmcnt(3)
	v_mfma_f32_16x16x32_bf16 v[70:73], v[216:219], v[50:53], v[70:73]
	ds_read_b128 v[216:219], v227 offset:192
	s_waitcnt lgkmcnt(3)
	v_mfma_f32_16x16x32_bf16 v[74:77], v[204:207], v[62:65], 0
	v_xor_b32_e32 v232, s30, v125
	v_lshlrev_b32_e32 v179, 4, v232
	v_or_b32_e32 v232, v179, v107
	v_mad_u32_u24 v226, v232, s96, v106
	ds_read_b128 v[204:207], v226
	s_waitcnt lgkmcnt(3)
	v_mfma_f32_16x16x32_bf16 v[74:77], v[208:211], v[58:61], v[74:77]
	ds_read_b128 v[208:211], v226 offset:64
	s_waitcnt lgkmcnt(3)
	v_mfma_f32_16x16x32_bf16 v[74:77], v[212:215], v[54:57], v[74:77]
	ds_read_b128 v[212:215], v226 offset:128
	s_waitcnt lgkmcnt(3)
	v_mfma_f32_16x16x32_bf16 v[74:77], v[216:219], v[50:53], v[74:77]
	ds_read_b128 v[216:219], v226 offset:192
	s_waitcnt lgkmcnt(3)
	v_mfma_f32_16x16x32_bf16 v[78:81], v[204:207], v[62:65], 0
	v_xor_b32_e32 v232, s30, v126
	v_lshl_or_b32 v232, v232, 4, v107
	v_mad_u32_u24 v227, v232, s96, v106
	ds_read_b128 v[204:207], v227
	s_waitcnt lgkmcnt(3)
	v_mfma_f32_16x16x32_bf16 v[78:81], v[208:211], v[58:61], v[78:81]
	ds_read_b128 v[208:211], v227 offset:64
	s_waitcnt lgkmcnt(3)
	v_mfma_f32_16x16x32_bf16 v[78:81], v[212:215], v[54:57], v[78:81]
	ds_read_b128 v[212:215], v227 offset:128
	s_waitcnt lgkmcnt(3)
	v_mfma_f32_16x16x32_bf16 v[78:81], v[216:219], v[50:53], v[78:81]
	ds_read_b128 v[216:219], v227 offset:192
	s_waitcnt lgkmcnt(3)
	v_mfma_f32_16x16x32_bf16 v[82:85], v[204:207], v[62:65], 0
	v_xor_b32_e32 v232, s30, v127
	v_lshlrev_b32_e32 v180, 4, v232
	v_or_b32_e32 v232, v180, v107
	v_mad_u32_u24 v226, v232, s96, v106
	ds_read_b128 v[204:207], v226
	s_waitcnt lgkmcnt(3)
	v_mfma_f32_16x16x32_bf16 v[82:85], v[208:211], v[58:61], v[82:85]
	ds_read_b128 v[208:211], v226 offset:64
	s_waitcnt lgkmcnt(3)
	v_mfma_f32_16x16x32_bf16 v[82:85], v[212:215], v[54:57], v[82:85]
	ds_read_b128 v[212:215], v226 offset:128
	s_waitcnt lgkmcnt(3)
	v_mfma_f32_16x16x32_bf16 v[82:85], v[216:219], v[50:53], v[82:85]
	ds_read_b128 v[216:219], v226 offset:192
	s_waitcnt lgkmcnt(3)
	v_mfma_f32_16x16x32_bf16 v[86:89], v[204:207], v[62:65], 0
	v_xor_b32_e32 v232, s30, v128
	v_lshl_or_b32 v232, v232, 4, v107
	v_mad_u32_u24 v227, v232, s96, v106
	ds_read_b128 v[204:207], v227
	s_waitcnt lgkmcnt(3)
	v_mfma_f32_16x16x32_bf16 v[86:89], v[208:211], v[58:61], v[86:89]
	ds_read_b128 v[208:211], v227 offset:64
	s_waitcnt lgkmcnt(3)
	v_mfma_f32_16x16x32_bf16 v[86:89], v[212:215], v[54:57], v[86:89]
	ds_read_b128 v[212:215], v227 offset:128
	s_waitcnt lgkmcnt(3)
	v_mfma_f32_16x16x32_bf16 v[86:89], v[216:219], v[50:53], v[86:89]
	ds_read_b128 v[216:219], v227 offset:192
	s_waitcnt lgkmcnt(3)
	v_mfma_f32_16x16x32_bf16 v[90:93], v[204:207], v[62:65], 0
	v_xor_b32_e32 v232, s30, v129
	v_lshlrev_b32_e32 v181, 4, v232
	v_or_b32_e32 v232, v181, v107
	v_mad_u32_u24 v226, v232, s96, v106
	ds_read_b128 v[204:207], v226
	s_waitcnt lgkmcnt(3)
	v_mfma_f32_16x16x32_bf16 v[90:93], v[208:211], v[58:61], v[90:93]
	ds_read_b128 v[208:211], v226 offset:64
	s_waitcnt lgkmcnt(3)
	v_mfma_f32_16x16x32_bf16 v[90:93], v[212:215], v[54:57], v[90:93]
	ds_read_b128 v[212:215], v226 offset:128
	s_waitcnt lgkmcnt(3)
	v_mfma_f32_16x16x32_bf16 v[90:93], v[216:219], v[50:53], v[90:93]
	ds_read_b128 v[216:219], v226 offset:192
	s_waitcnt lgkmcnt(3)
	v_mfma_f32_16x16x32_bf16 v[94:97], v[204:207], v[62:65], 0
	v_xor_b32_e32 v232, s30, v130
	v_lshl_or_b32 v232, v232, 4, v107
	v_mad_u32_u24 v227, v232, s96, v106
	ds_read_b128 v[204:207], v227
	s_waitcnt lgkmcnt(3)
	v_mfma_f32_16x16x32_bf16 v[94:97], v[208:211], v[58:61], v[94:97]
	ds_read_b128 v[208:211], v227 offset:64
	s_waitcnt lgkmcnt(3)
	v_mfma_f32_16x16x32_bf16 v[94:97], v[212:215], v[54:57], v[94:97]
	ds_read_b128 v[212:215], v227 offset:128
	s_waitcnt lgkmcnt(3)
	v_mfma_f32_16x16x32_bf16 v[94:97], v[216:219], v[50:53], v[94:97]
	ds_read_b128 v[216:219], v227 offset:192
	s_waitcnt lgkmcnt(3)
	v_mfma_f32_16x16x32_bf16 v[98:101], v[204:207], v[62:65], 0
	v_xor_b32_e32 v232, s30, v131
	v_lshlrev_b32_e32 v182, 4, v232
	v_or_b32_e32 v232, v182, v107
	v_mad_u32_u24 v226, v232, s96, v106
	ds_read_b128 v[204:207], v226
	s_waitcnt lgkmcnt(3)
	v_mfma_f32_16x16x32_bf16 v[98:101], v[208:211], v[58:61], v[98:101]
	ds_read_b128 v[208:211], v226 offset:64
	s_waitcnt lgkmcnt(3)
	v_mfma_f32_16x16x32_bf16 v[98:101], v[212:215], v[54:57], v[98:101]
	ds_read_b128 v[212:215], v226 offset:128
	s_waitcnt lgkmcnt(3)
	v_mfma_f32_16x16x32_bf16 v[98:101], v[216:219], v[50:53], v[98:101]
	ds_read_b128 v[216:219], v226 offset:192
	s_waitcnt lgkmcnt(3)
	v_mfma_f32_16x16x32_bf16 v[102:105], v[204:207], v[62:65], 0
	s_waitcnt lgkmcnt(2)
	v_mfma_f32_16x16x32_bf16 v[102:105], v[208:211], v[58:61], v[102:105]
	s_waitcnt lgkmcnt(1)
	v_mfma_f32_16x16x32_bf16 v[102:105], v[212:215], v[54:57], v[102:105]
	s_waitcnt lgkmcnt(0)
	v_mfma_f32_16x16x32_bf16 v[102:105], v[216:219], v[50:53], v[102:105]
	s_branch .Lattn_qk_done
.Lattn_qk_odd:
	v_mov_b32_e32 v70, 0
	v_mov_b32_e32 v71, 0
	v_mov_b32_e32 v72, 0
	v_mov_b32_e32 v73, 0
	v_bitop3_b32 v232, s31, v111, 8 bitop3:0x6c
	v_lshlrev_b32_e32 v178, 4, v232
	v_xor_b32_e32 v232, s30, v124
	v_lshl_or_b32 v232, v232, 4, v107
	v_mad_u32_u24 v227, v232, s96, v106
	ds_read_b128 v[204:207], v227
	ds_read_b128 v[208:211], v227 offset:64
	ds_read_b128 v[212:215], v227 offset:128
	ds_read_b128 v[216:219], v227 offset:192
	s_waitcnt lgkmcnt(3)
	v_mfma_f32_16x16x32_bf16 v[74:77], v[204:207], v[62:65], 0
	v_xor_b32_e32 v232, s30, v125
	v_lshlrev_b32_e32 v179, 4, v232
	v_or_b32_e32 v232, v179, v107
	v_mad_u32_u24 v226, v232, s96, v106
	ds_read_b128 v[204:207], v226
	s_waitcnt lgkmcnt(3)
	v_mfma_f32_16x16x32_bf16 v[74:77], v[208:211], v[58:61], v[74:77]
	ds_read_b128 v[208:211], v226 offset:64
	s_waitcnt lgkmcnt(3)
	v_mfma_f32_16x16x32_bf16 v[74:77], v[212:215], v[54:57], v[74:77]
	ds_read_b128 v[212:215], v226 offset:128
	s_waitcnt lgkmcnt(3)
	v_mfma_f32_16x16x32_bf16 v[74:77], v[216:219], v[50:53], v[74:77]
	ds_read_b128 v[216:219], v226 offset:192
	s_waitcnt lgkmcnt(3)
	v_mfma_f32_16x16x32_bf16 v[78:81], v[204:207], v[62:65], 0
	v_xor_b32_e32 v232, s30, v126
	v_lshl_or_b32 v232, v232, 4, v107
	v_mad_u32_u24 v227, v232, s96, v106
	ds_read_b128 v[204:207], v227
	s_waitcnt lgkmcnt(3)
	v_mfma_f32_16x16x32_bf16 v[78:81], v[208:211], v[58:61], v[78:81]
	ds_read_b128 v[208:211], v227 offset:64
	s_waitcnt lgkmcnt(3)
	v_mfma_f32_16x16x32_bf16 v[78:81], v[212:215], v[54:57], v[78:81]
	ds_read_b128 v[212:215], v227 offset:128
	s_waitcnt lgkmcnt(3)
	v_mfma_f32_16x16x32_bf16 v[78:81], v[216:219], v[50:53], v[78:81]
	ds_read_b128 v[216:219], v227 offset:192
	s_waitcnt lgkmcnt(3)
	v_mfma_f32_16x16x32_bf16 v[82:85], v[204:207], v[62:65], 0
	v_xor_b32_e32 v232, s30, v127
	v_lshlrev_b32_e32 v180, 4, v232
	v_or_b32_e32 v232, v180, v107
	v_mad_u32_u24 v226, v232, s96, v106
	ds_read_b128 v[204:207], v226
	s_waitcnt lgkmcnt(3)
	v_mfma_f32_16x16x32_bf16 v[82:85], v[208:211], v[58:61], v[82:85]
	ds_read_b128 v[208:211], v226 offset:64
	s_waitcnt lgkmcnt(3)
	v_mfma_f32_16x16x32_bf16 v[82:85], v[212:215], v[54:57], v[82:85]
	ds_read_b128 v[212:215], v226 offset:128
	s_waitcnt lgkmcnt(3)
	v_mfma_f32_16x16x32_bf16 v[82:85], v[216:219], v[50:53], v[82:85]
	ds_read_b128 v[216:219], v226 offset:192
	s_waitcnt lgkmcnt(3)
	v_mfma_f32_16x16x32_bf16 v[86:89], v[204:207], v[62:65], 0
	v_xor_b32_e32 v232, s30, v128
	v_lshl_or_b32 v232, v232, 4, v107
	v_mad_u32_u24 v227, v232, s96, v106
	ds_read_b128 v[204:207], v227
	s_waitcnt lgkmcnt(3)
	v_mfma_f32_16x16x32_bf16 v[86:89], v[208:211], v[58:61], v[86:89]
	ds_read_b128 v[208:211], v227 offset:64
	s_waitcnt lgkmcnt(3)
	v_mfma_f32_16x16x32_bf16 v[86:89], v[212:215], v[54:57], v[86:89]
	ds_read_b128 v[212:215], v227 offset:128
	s_waitcnt lgkmcnt(3)
	v_mfma_f32_16x16x32_bf16 v[86:89], v[216:219], v[50:53], v[86:89]
	ds_read_b128 v[216:219], v227 offset:192
	s_waitcnt lgkmcnt(3)
	v_mfma_f32_16x16x32_bf16 v[90:93], v[204:207], v[62:65], 0
	v_xor_b32_e32 v232, s30, v129
	v_lshlrev_b32_e32 v181, 4, v232
	v_or_b32_e32 v232, v181, v107
	v_mad_u32_u24 v226, v232, s96, v106
	ds_read_b128 v[204:207], v226
	s_waitcnt lgkmcnt(3)
	v_mfma_f32_16x16x32_bf16 v[90:93], v[208:211], v[58:61], v[90:93]
	ds_read_b128 v[208:211], v226 offset:64
	s_waitcnt lgkmcnt(3)
	v_mfma_f32_16x16x32_bf16 v[90:93], v[212:215], v[54:57], v[90:93]
	ds_read_b128 v[212:215], v226 offset:128
	s_waitcnt lgkmcnt(3)
	v_mfma_f32_16x16x32_bf16 v[90:93], v[216:219], v[50:53], v[90:93]
	ds_read_b128 v[216:219], v226 offset:192
	s_waitcnt lgkmcnt(3)
	v_mfma_f32_16x16x32_bf16 v[94:97], v[204:207], v[62:65], 0
	v_xor_b32_e32 v232, s30, v130
	v_lshl_or_b32 v232, v232, 4, v107
	v_mad_u32_u24 v227, v232, s96, v106
	ds_read_b128 v[204:207], v227
	s_waitcnt lgkmcnt(3)
	v_mfma_f32_16x16x32_bf16 v[94:97], v[208:211], v[58:61], v[94:97]
	ds_read_b128 v[208:211], v227 offset:64
	s_waitcnt lgkmcnt(3)
	v_mfma_f32_16x16x32_bf16 v[94:97], v[212:215], v[54:57], v[94:97]
	ds_read_b128 v[212:215], v227 offset:128
	s_waitcnt lgkmcnt(3)
	v_mfma_f32_16x16x32_bf16 v[94:97], v[216:219], v[50:53], v[94:97]
	ds_read_b128 v[216:219], v227 offset:192
	s_waitcnt lgkmcnt(3)
	v_mfma_f32_16x16x32_bf16 v[98:101], v[204:207], v[62:65], 0
	v_xor_b32_e32 v232, s30, v131
	v_lshlrev_b32_e32 v182, 4, v232
	v_or_b32_e32 v232, v182, v107
	v_mad_u32_u24 v226, v232, s96, v106
	ds_read_b128 v[204:207], v226
	s_waitcnt lgkmcnt(3)
	v_mfma_f32_16x16x32_bf16 v[98:101], v[208:211], v[58:61], v[98:101]
	ds_read_b128 v[208:211], v226 offset:64
	s_waitcnt lgkmcnt(3)
	v_mfma_f32_16x16x32_bf16 v[98:101], v[212:215], v[54:57], v[98:101]
	ds_read_b128 v[212:215], v226 offset:128
	s_waitcnt lgkmcnt(3)
	v_mfma_f32_16x16x32_bf16 v[98:101], v[216:219], v[50:53], v[98:101]
	ds_read_b128 v[216:219], v226 offset:192
	s_waitcnt lgkmcnt(3)
	v_mfma_f32_16x16x32_bf16 v[102:105], v[204:207], v[62:65], 0
	v_xor_b32_e32 v232, s30, v132
	v_lshl_or_b32 v232, v232, 4, v107
	v_mad_u32_u24 v227, v232, s96, v106
	ds_read_b128 v[204:207], v227
	s_waitcnt lgkmcnt(3)
	v_mfma_f32_16x16x32_bf16 v[102:105], v[208:211], v[58:61], v[102:105]
	ds_read_b128 v[208:211], v227 offset:64
	s_waitcnt lgkmcnt(3)
	v_mfma_f32_16x16x32_bf16 v[102:105], v[212:215], v[54:57], v[102:105]
	ds_read_b128 v[212:215], v227 offset:128
	s_waitcnt lgkmcnt(3)
	v_mfma_f32_16x16x32_bf16 v[102:105], v[216:219], v[50:53], v[102:105]
	ds_read_b128 v[216:219], v227 offset:192
	s_waitcnt lgkmcnt(3)
	v_mfma_f32_16x16x32_bf16 v[66:69], v[204:207], v[62:65], 0
	s_waitcnt lgkmcnt(2)
	v_mfma_f32_16x16x32_bf16 v[66:69], v[208:211], v[58:61], v[66:69]
	s_waitcnt lgkmcnt(1)
	v_mfma_f32_16x16x32_bf16 v[66:69], v[212:215], v[54:57], v[66:69]
	s_waitcnt lgkmcnt(0)
	v_mfma_f32_16x16x32_bf16 v[66:69], v[216:219], v[50:53], v[66:69]
.Lattn_qk_done:
	s_mov_b64 s[24:25], exec
